# start-up copy of the latent input into the residual buffer folded into layer 0's first pre-norm pass (reads the input tensor, stores raw rows to out); separate 268 MB copy loop removed
# speedup vs baseline: 1.0024x; 1.0024x over previous
; __device__ __forceinline__ void phase_pre(KArgs& a, LAS unsigned char* lds) {
;     ...
;     for (size_t i = gt; i < (size_t)NB * SEQ * DM / 4; i += gn) ((f32x4*)a.out)[i] = ((const f32x4*)a.x)[i];
;     for (size_t i = gt; i < (size_t)NB * CTXL * DM / 4; i += gn) ((f32x4*)(a.ws + OFF_XC))[i] = ((const f32x4*)a.ctx)[i];
.LBB0_17:
	v_readlane_b32 s0, v237, 0
	v_readlane_b32 s1, v237, 1
	s_load_dword s4, s[0:1], 0x10
	s_load_dword s5, s[0:1], 0x0
	s_ashr_i32 s23, s22, 31
	s_lshl_b64 s[0:1], s[22:23], 9
	v_lshl_add_u64 v[2:3], s[0:1], 0, v[34:35]
	s_waitcnt lgkmcnt(0)
	s_lshr_b32 s0, s4, 16
	s_cmp_lg_u32 s0, 0
	s_cselect_b64 s[0:1], -1, 0
	s_cmp_lg_u64 s[0:1], 0
	s_addc_u32 s24, s5, 0
	s_ashr_i32 s25, s24, 31
	s_mov_b64 s[4:5], 0x800000
	s_lshl_b64 s[0:1], s[24:25], 9
	v_cmp_gt_u64_e32 vcc, s[4:5], v[2:3]
	s_and_saveexec_b64 s[4:5], vcc
	s_branch .LBB0_20

; #define LAS __attribute__((address_space(3)))
; __device__ __forceinline__ int tid_() { int t = threadIdx.x; asm volatile("" : "+v"(t)); return t; }
; __device__ __forceinline__ int bid_() { int t = blockIdx.x; asm volatile("" : "+s"(t)); return t; }
; __device__ __forceinline__ int nblk_() { int t = gridDim.x; asm volatile("" : "+s"(t)); return t; }
; __device__ __forceinline__ void prenorm_all(KArgs& a, LAS unsigned char* lds, const float* g, const float* mods_l, int si, bf16_t* Hn, const float* PB) {
;     LAS unsigned char* tmap = lds + 140000;
;     if (PB) build_tmap(tmap);
;     const int lane = tid_() & 63, gw = bid_() * 8 + (tid_() >> 6), ngw = nblk_() * 8;
;     for (int r = gw; r < MTOK; r += ngw) {
;         const int b = r / TPB, t = r - b * TPB; const float* md = mods_l + (size_t)(t < CTXL ? 8 : b) * 6144;
;         prenorm_row(xrow(a, r), g, md + si * DM, md + (si + 1) * DM, Hn + (size_t)r * DM, lane, tmap, PB, r);
.LBB0_216:
	v_mov_b64_e32 v[2:3], 0
	s_load_dwordx2 s[0:1], s[42:43], 0x0
	s_load_dwordx2 s[100:101], s[42:43], 0xd8
	v_cmp_ne_u64_e64 s[40:41], 0, v[2:3]
	s_and_saveexec_b64 s[4:5], s[40:41]
	s_cbranch_execz .LBB0_223

; #define LAS __attribute__((address_space(3)))
; __device__ __forceinline__ int tid_() { int t = threadIdx.x; asm volatile("" : "+v"(t)); return t; }
; __device__ __forceinline__ int bid_() { int t = blockIdx.x; asm volatile("" : "+s"(t)); return t; }
; __device__ __forceinline__ int nblk_() { int t = gridDim.x; asm volatile("" : "+s"(t)); return t; }
; __device__ __forceinline__ void prenorm_row(float* xr, const float* g, const float* shift, const float* scale, bf16_t* orow, int lane, const LAS unsigned char* tmap, const float* PB, int r) {
;     f32x4 v[4]; float s = 0.f;
; #pragma unroll
;     for (int j = 0; j < 4; ++j) v[j] = ((const f32x4*)xr)[lane + 64 * j];
; __device__ __forceinline__ void prenorm_all(KArgs& a, LAS unsigned char* lds, const float* g, const float* mods_l, int si, bf16_t* Hn, const float* PB) {
;     LAS unsigned char* tmap = lds + 140000;
;     if (PB) build_tmap(tmap);
;     const int lane = tid_() & 63, gw = bid_() * 8 + (tid_() >> 6), ngw = nblk_() * 8;
;     for (int r = gw; r < MTOK; r += ngw) {
;         const int b = r / TPB, t = r - b * TPB; const float* md = mods_l + (size_t)(t < CTXL ? 8 : b) * 6144;
;         prenorm_row(xrow(a, r), g, md + si * DM, md + (si + 1) * DM, Hn + (size_t)r * DM, lane, tmap, PB, r);
.LBB0_223:
	s_or_b64 exec, exec, s[4:5]
	v_readlane_b32 s8, v237, 2
	v_mov_b32_e32 v0, v216
	s_mov_b32 s2, s84
	v_mov_b32_e32 v4, v216
	v_readlane_b32 s9, v237, 3
	s_load_dwordx2 s[4:5], s[8:9], 0xf0
	v_ashrrev_i32_e32 v4, 6, v4
	v_lshl_add_u32 v20, s2, 3, v4
	v_cmp_gt_i32_e32 vcc, s88, v20
	s_waitcnt lgkmcnt(0)
	s_sub_u32 s100, s100, s0
	s_subb_u32 s101, s101, s1
	s_mov_b32 s3, s4
	s_and_saveexec_b64 s[4:5], vcc
	s_cbranch_execz .LBB0_238
	v_and_b32_e32 v24, 63, v0
	v_lshlrev_b32_e32 v0, 4, v24
	v_lshl_add_u64 v[26:27], v[2:3], 0, v[0:1]
	v_and_b32_e32 v2, 64, v217
	v_add_u32_e32 v2, 64, v2
	v_xor_b32_e32 v3, 1, v217
	v_cmp_lt_i32_e32 vcc, v3, v2
	s_lshl_b32 s18, s14, 10
	s_ashr_i32 s19, s18, 31
	v_cndmask_b32_e32 v3, v217, v3, vcc
	v_lshlrev_b32_e32 v25, 2, v3
	v_xor_b32_e32 v3, 2, v217
	v_cmp_lt_i32_e32 vcc, v3, v2
	s_lshl_b32 s8, s3, 3
	s_lshl_b64 s[18:19], s[18:19], 2
	v_cndmask_b32_e32 v3, v217, v3, vcc
	v_lshlrev_b32_e32 v42, 2, v3
	v_xor_b32_e32 v3, 4, v217
	v_cmp_lt_i32_e32 vcc, v3, v2
	s_add_u32 s16, s16, s18
	v_mad_i64_i32 v[6:7], s[14:15], s14, v226, v[18:19]
	v_cndmask_b32_e32 v3, v217, v3, vcc
	v_lshlrev_b32_e32 v43, 2, v3
	v_xor_b32_e32 v3, 8, v217
	v_cmp_lt_i32_e32 vcc, v3, v2
	s_addc_u32 s17, s17, s19
	s_mov_b64 s[14:15], 0x800000
	v_cndmask_b32_e32 v3, v217, v3, vcc
	v_lshlrev_b32_e32 v44, 2, v3
	v_xor_b32_e32 v3, 16, v217
	v_cmp_lt_i32_e32 vcc, v3, v2
	v_ashrrev_i32_e32 v21, 31, v20
	v_lshl_add_u64 v[22:23], v[6:7], 0, s[14:15]
	v_cndmask_b32_e32 v3, v217, v3, vcc
	v_lshlrev_b32_e32 v45, 2, v3
	v_xor_b32_e32 v3, 32, v217
	v_cmp_lt_i32_e32 vcc, v3, v2
	v_or_b32_e32 v6, 64, v24
	v_or_b32_e32 v8, 0x80, v24
	v_or_b32_e32 v10, 0xc0, v24
	v_cndmask_b32_e32 v2, v217, v3, vcc
	v_lshl_add_u64 v[28:29], s[16:17], 0, v[0:1]
	v_lshlrev_b32_e32 v0, 8, v4
	v_lshlrev_b64 v[30:31], 11, v[20:21]
	s_ashr_i32 s9, s8, 31
	v_lshlrev_b32_e32 v46, 2, v2
	v_lshl_add_u32 v47, s2, 11, v0
	s_lshl_b32 s2, s3, 11
	v_lshl_or_b32 v30, v24, 3, v30
	s_lshl_b64 s[14:15], s[8:9], 11
	s_mov_b64 s[16:17], 0
	v_lshlrev_b32_e32 v32, 4, v6
	v_lshlrev_b32_e32 v34, 4, v8
	v_lshlrev_b32_e32 v36, 4, v10
	s_branch .LBB0_227

; #define LAS __attribute__((address_space(3)))
; __device__ __forceinline__ unsigned pk2(float lo, float hi) { const f32x2 v = {lo, hi}; return __builtin_bit_cast(unsigned, __builtin_convertvector(v, bf16v2_t)); }
; __device__ __forceinline__ void prenorm_row(float* xr, const float* g, const float* shift, const float* scale, bf16_t* orow, int lane, const LAS unsigned char* tmap, const float* PB, int r) {
;     f32x4 v[4]; float s = 0.f;
; #pragma unroll
;     for (int j = 0; j < 4; ++j) v[j] = ((const f32x4*)xr)[lane + 64 * j];
;     if (PB) { if (fold_partials(v, tmap, PB, r, lane)) {
; #pragma unroll
;         for (int j = 0; j < 4; ++j) ((f32x4*)xr)[lane + 64 * j] = v[j]; } }
; #pragma unroll
;     for (int j = 0; j < 4; ++j) s += (v[j].x * v[j].x + v[j].y * v[j].y) + (v[j].z * v[j].z + v[j].w * v[j].w);
;     const float rstd = rsqrtf(wave_sum(s) * (1.f / DM) + 1e-6f);
; #pragma unroll
;     for (int j = 0; j < 4; ++j) {
;         const f32x4 gg = ((const f32x4*)g)[lane + 64 * j], sh = ((const f32x4*)shift)[lane + 64 * j], sc = ((const f32x4*)scale)[lane + 64 * j];
;         const f32x4 y = v[j] * rstd * gg * (sc + 1.f) + sh;
;         u32x2 o; o.x = pk2(y.x, y.y); o.y = pk2(y.z, y.w);
;         ((u32x2*)orow)[lane + 64 * j] = o;
;     }
.LBB0_226:
	s_andn2_saveexec_b64 s[22:23], s[22:23]
	s_or_b64 exec, exec, s[22:23]
	v_cndmask_b32_e64 v21, v38, 8, s[42:43]
	v_mul_hi_i32_i24_e32 v39, 0x6000, v21
	v_mul_i32_i24_e32 v38, 0x6000, v21
	v_lshl_add_u64 v[52:53], v[22:23], 0, v[38:39]
	s_mov_b64 s[18:19], 0x1000
	v_lshl_add_u64 v[56:57], v[52:53], 0, s[18:19]
	v_lshl_add_u64 v[48:49], v[56:57], 0, v[0:1]
	global_load_dwordx4 v[38:41], v[28:29], off
	v_lshl_add_u64 v[58:59], v[52:53], 0, v[0:1]
	global_load_dwordx4 v[48:51], v[48:49], off
	s_waitcnt vmcnt(0)
	v_readlane_b32 s3, v236, 27
	s_nop 3
	s_cmp_lg_u32 s3, 0
	s_cbranch_scc1 .Lpa_nost
	s_andn2_b64 exec, exec, s[42:43]
	global_store_dwordx4 v[190:191], v[14:17], off
	global_store_dwordx4 v[190:191], v[10:13], off offset:1024
	global_store_dwordx4 v[190:191], v[6:9], off offset:2048
	global_store_dwordx4 v[190:191], v[2:5], off offset:3072
	s_or_b64 exec, exec, s[42:43]
.Lpa_nost:
	v_pk_mul_f32 v[60:61], v[12:13], v[12:13]
	global_load_dwordx4 v[52:55], v[58:59], off
	v_pk_mul_f32 v[62:63], v[10:11], v[10:11]
	v_pk_mul_f32 v[64:65], v[16:17], v[16:17]
	v_pk_mul_f32 v[66:67], v[14:15], v[14:15]
	s_waitcnt vmcnt(4)
	v_mul_f32_e32 v0, v6, v6
	v_pk_mov_b32 v[70:71], v[66:67], v[64:65] op_sel:[1,0]
	v_mov_b32_e32 v67, v65
	v_pk_mov_b32 v[64:65], v[62:63], v[60:61] op_sel:[1,0]
	v_mov_b32_e32 v63, v61
	v_mul_f32_e32 v68, v8, v8
	v_pk_add_f32 v[66:67], v[70:71], v[66:67]
	v_pk_add_f32 v[62:63], v[64:65], v[62:63]
	v_pk_fma_f32 v[60:61], v[6:7], v[6:7], v[0:1] op_sel_hi:[1,1,0]
	v_pk_fma_f32 v[68:69], v[8:9], v[8:9], v[68:69] op_sel_hi:[1,1,0]
	v_pk_add_f32 v[64:65], v[66:67], v[66:67] op_sel_hi:[0,1]
	v_pk_add_f32 v[62:63], v[62:63], v[62:63] op_sel_hi:[0,1]
	s_waitcnt vmcnt(3)
	v_mul_f32_e32 v60, v2, v2
	v_mul_f32_e32 v68, v3, v3
	v_mul_f32_e32 v64, v4, v4
	v_mul_f32_e32 v62, v5, v5
	v_pk_add_f32 v[60:61], v[60:61], v[68:69]
	v_pk_add_f32 v[62:63], v[64:65], v[62:63]
	s_mov_b32 s3, 0x800000
	v_pk_add_f32 v[60:61], v[60:61], v[62:63]
	v_mov_b32_e32 v33, v1
	v_add_f32_e32 v0, v60, v61
	ds_bpermute_b32 v21, v25, v0
	v_lshl_add_u64 v[60:61], v[18:19], 0, v[30:31]
	v_mov_b32_e32 v35, v1
	v_mov_b32_e32 v37, v1
	v_lshl_add_u64 v[184:185], v[56:57], 0, v[32:33]
	v_lshl_add_u64 v[186:187], v[56:57], 0, v[34:35]
	v_lshl_add_u64 v[188:189], v[56:57], 0, v[36:37]
	global_load_dwordx4 v[148:151], v[28:29], off offset:1024
	global_load_dwordx4 v[152:155], v[184:185], off
	global_load_dwordx4 v[156:159], v[58:59], off offset:1024
	global_load_dwordx4 v[160:163], v[28:29], off offset:2048
	global_load_dwordx4 v[164:167], v[186:187], off
	global_load_dwordx4 v[168:171], v[58:59], off offset:2048
	global_load_dwordx4 v[172:175], v[28:29], off offset:3072
	global_load_dwordx4 v[176:179], v[188:189], off
	global_load_dwordx4 v[180:183], v[58:59], off offset:3072
	v_add_u32_e32 v20, s8, v20
	s_waitcnt lgkmcnt(0)
	v_add_f32_e32 v0, v0, v21
	ds_bpermute_b32 v21, v42, v0
	v_add_u32_e32 v47, s2, v47
	v_lshl_add_u64 v[30:31], v[30:31], 0, s[14:15]
	s_waitcnt lgkmcnt(0)
	v_add_f32_e32 v0, v0, v21
	ds_bpermute_b32 v21, v43, v0
	s_waitcnt lgkmcnt(0)
	v_add_f32_e32 v0, v0, v21
	ds_bpermute_b32 v21, v44, v0
	s_waitcnt lgkmcnt(0)
	v_add_f32_e32 v0, v0, v21
	ds_bpermute_b32 v21, v45, v0
	s_waitcnt lgkmcnt(0)
	v_add_f32_e32 v0, v0, v21
	ds_bpermute_b32 v21, v46, v0
	s_waitcnt lgkmcnt(0)
	v_add_f32_e32 v0, v0, v21
	v_fmamk_f32 v0, v0, 0x3a800000, v219
	v_mul_f32_e32 v21, 0x4b800000, v0
	v_cmp_gt_f32_e32 vcc, s3, v0
	s_mov_b32 s3, 0x33f8000
	v_add_co_u32_e64 v60, s[42:43], s3, v60
	v_cndmask_b32_e32 v0, v0, v21, vcc
	v_rsq_f32_e32 v0, v0
	v_addc_co_u32_e64 v61, s[42:43], 0, v61, s[42:43]
	s_mov_b32 s3, 0x87ff
	v_mul_f32_e32 v21, 0x45800000, v0
	v_cndmask_b32_e32 v0, v0, v21, vcc
	v_pk_mul_f32 v[16:17], v[16:17], v[0:1] op_sel_hi:[1,0]
	v_pk_mul_f32 v[14:15], v[14:15], v[0:1] op_sel_hi:[1,0]
	s_waitcnt vmcnt(10)
	v_pk_mul_f32 v[16:17], v[40:41], v[16:17]
	v_pk_mul_f32 v[14:15], v[38:39], v[14:15]
	v_pk_add_f32 v[38:39], v[50:51], 1.0 op_sel_hi:[1,0]
	v_pk_add_f32 v[40:41], v[48:49], 1.0 op_sel_hi:[1,0]
	s_waitcnt vmcnt(9)
	v_pk_fma_f32 v[16:17], v[38:39], v[16:17], v[54:55]
	v_pk_fma_f32 v[14:15], v[40:41], v[14:15], v[52:53]
	s_nop 0
	v_cvt_pk_bf16_f32 v14, v14, v15
	v_cvt_pk_bf16_f32 v15, v16, v17
	global_store_dwordx2 v[60:61], v[14:15], off
	v_pk_mul_f32 v[12:13], v[12:13], v[0:1] op_sel_hi:[1,0]
	v_pk_mul_f32 v[10:11], v[10:11], v[0:1] op_sel_hi:[1,0]
	v_pk_mul_f32 v[8:9], v[8:9], v[0:1] op_sel_hi:[1,0]
	v_pk_mul_f32 v[6:7], v[6:7], v[0:1] op_sel_hi:[1,0]
	v_pk_mul_f32 v[4:5], v[4:5], v[0:1] op_sel_hi:[1,0]
	v_pk_mul_f32 v[2:3], v[2:3], v[0:1] op_sel_hi:[1,0]
	v_cmp_lt_i32_e32 vcc, s3, v20
	s_or_b64 s[16:17], vcc, s[16:17]
	s_waitcnt vmcnt(9)
	v_pk_mul_f32 v[10:11], v[148:149], v[10:11]
	v_pk_mul_f32 v[12:13], v[150:151], v[12:13]
	s_waitcnt vmcnt(8)
	v_pk_add_f32 v[14:15], v[154:155], 1.0 op_sel_hi:[1,0]
	v_pk_add_f32 v[16:17], v[152:153], 1.0 op_sel_hi:[1,0]
	s_waitcnt vmcnt(7)
	v_pk_fma_f32 v[12:13], v[14:15], v[12:13], v[158:159]
	v_pk_fma_f32 v[10:11], v[16:17], v[10:11], v[156:157]
	s_nop 0
	v_cvt_pk_bf16_f32 v10, v10, v11
	v_cvt_pk_bf16_f32 v11, v12, v13
	global_store_dwordx2 v[60:61], v[10:11], off offset:512
	s_waitcnt vmcnt(7)
	v_pk_mul_f32 v[6:7], v[160:161], v[6:7]
	v_pk_mul_f32 v[8:9], v[162:163], v[8:9]
	s_waitcnt vmcnt(6)
	v_pk_add_f32 v[10:11], v[166:167], 1.0 op_sel_hi:[1,0]
	v_pk_add_f32 v[12:13], v[164:165], 1.0 op_sel_hi:[1,0]
	s_waitcnt vmcnt(5)
	v_pk_fma_f32 v[8:9], v[10:11], v[8:9], v[170:171]
	v_pk_fma_f32 v[6:7], v[12:13], v[6:7], v[168:169]
	s_nop 0
	v_cvt_pk_bf16_f32 v6, v6, v7
	v_cvt_pk_bf16_f32 v7, v8, v9
	global_store_dwordx2 v[60:61], v[6:7], off offset:1024
	s_waitcnt vmcnt(5)
	v_pk_mul_f32 v[2:3], v[172:173], v[2:3]
	v_pk_mul_f32 v[4:5], v[174:175], v[4:5]
	s_waitcnt vmcnt(4)
	v_pk_add_f32 v[6:7], v[178:179], 1.0 op_sel_hi:[1,0]
	v_pk_add_f32 v[8:9], v[176:177], 1.0 op_sel_hi:[1,0]
	s_waitcnt vmcnt(3)
	v_pk_fma_f32 v[4:5], v[6:7], v[4:5], v[182:183]
	v_pk_fma_f32 v[2:3], v[8:9], v[2:3], v[180:181]
	s_nop 0
	v_cvt_pk_bf16_f32 v2, v2, v3
	v_cvt_pk_bf16_f32 v3, v4, v5
	global_store_dwordx2 v[60:61], v[2:3], off offset:1536
	s_andn2_b64 exec, exec, s[16:17]
	s_cbranch_execz .LBB0_238
; __device__ __forceinline__ void prenorm_all(KArgs& a, LAS unsigned char* lds, const float* g, const float* mods_l, int si, bf16_t* Hn, const float* PB) {
;     ...
;     for (int r = gw; r < MTOK; r += ngw) {
;         const int b = r / TPB, t = r - b * TPB; const float* md = mods_l + (size_t)(t < CTXL ? 8 : b) * 6144;
;         prenorm_row(xrow(a, r), g, md + si * DM, md + (si + 1) * DM, Hn + (size_t)r * DM, lane, tmap, PB, r);
.LBB0_227:
	v_mul_hi_i32 v0, v20, s89
	v_lshrrev_b32_e32 v2, 31, v0
	v_ashrrev_i32_e32 v0, 11, v0
	v_add_u32_e32 v38, v0, v2
	s_movk_i32 s3, 0xef00
	v_mad_i32_i24 v0, v38, s3, v20
	v_add_u32_e32 v4, 0xffffff00, v0
	v_mov_b32_e32 v2, s1
	v_cmp_gt_i32_e64 s[42:43], s96, v0
	v_ashrrev_i32_e32 v39, 31, v38
	v_ashrrev_i32_e32 v5, 31, v0
	v_cndmask_b32_e64 v3, v2, v19, s[42:43]
	v_mov_b32_e32 v2, s0
	v_cndmask_b32_e64 v4, v4, v0, s[42:43]
	v_cndmask_b32_e64 v0, 24, 20, s[42:43]
	v_cndmask_b32_e64 v2, v2, v18, s[42:43]
	v_cndmask_b32_e64 v5, 0, v5, s[42:43]
	v_lshlrev_b64 v[6:7], v0, v[38:39]
	v_lshl_add_u64 v[2:3], v[2:3], 0, v[6:7]
	v_lshlrev_b64 v[4:5], 12, v[4:5]
	v_lshl_add_u64 v[2:3], v[2:3], 0, v[4:5]
	v_lshlrev_b32_e32 v0, 4, v24
	v_lshl_add_u64 v[40:41], v[2:3], 0, v[0:1]
	v_lshl_add_u64 v[190:191], v[40:41], 0, s[100:101]
	global_load_dwordx4 v[14:17], v[40:41], off
	global_load_dwordx4 v[10:13], v[40:41], off offset:1024
	global_load_dwordx4 v[6:9], v[40:41], off offset:2048
	global_load_dwordx4 v[2:5], v[40:41], off offset:3072
	s_and_saveexec_b64 s[18:19], s[40:41]
	s_xor_b64 s[22:23], exec, s[18:19]
	s_cbranch_execz .LBB0_226
	v_ashrrev_i32_e32 v21, 6, v20
	v_and_b32_e32 v33, -4, v21
	v_add_u32_e32 v21, 0, v33
	v_add_u32_e32 v21, 0x222e0, v21
	ds_read_u8 v35, v21
	v_and_b32_e32 v21, 0xff00, v47
	v_lshlrev_b32_e32 v21, 2, v21
	s_waitcnt lgkmcnt(0)
	v_cmp_ne_u16_e64 s[24:25], s90, v35
	s_and_saveexec_b64 s[34:35], s[24:25]
	s_cbranch_execz .LBB0_230
	v_lshl_or_b32 v48, v35, 18, v21
	v_mov_b32_e32 v49, v1
	v_lshl_add_u64 v[60:61], v[26:27], 0, v[48:49]
	v_add_co_u32_e32 v52, vcc, 0x800000, v60
	s_nop 1
	v_addc_co_u32_e32 v53, vcc, 0, v61, vcc
	v_add_co_u32_e32 v56, vcc, 0x1000000, v60
	global_load_dwordx4 v[48:51], v[60:61], off
	s_nop 0
	global_load_dwordx4 v[52:55], v[52:53], off
	v_addc_co_u32_e32 v57, vcc, 0, v61, vcc
	v_add_co_u32_e32 v60, vcc, 0x1800000, v60
	global_load_dwordx4 v[56:59], v[56:57], off
	s_nop 0
	v_addc_co_u32_e32 v61, vcc, 0, v61, vcc
	global_load_dwordx4 v[60:63], v[60:61], off
	s_waitcnt vmcnt(0)
	v_pk_add_f32 v[16:17], v[16:17], v[50:51]
	v_pk_add_f32 v[14:15], v[14:15], v[48:49]
	s_waitcnt vmcnt(2)
	v_pk_add_f32 v[16:17], v[54:55], v[16:17]
	v_pk_add_f32 v[14:15], v[52:53], v[14:15]
	s_waitcnt vmcnt(1)
	v_pk_add_f32 v[16:17], v[58:59], v[16:17]
	v_pk_add_f32 v[14:15], v[56:57], v[14:15]
	s_waitcnt vmcnt(0)
	v_pk_add_f32 v[16:17], v[62:63], v[16:17]
	v_pk_add_f32 v[14:15], v[60:61], v[14:15]
